# MLA prep: rotary-part q/k stores widened dwordx2 pairs -> dwordx4 via DPP lane-pair exchange
# baseline (speedup 1.0000x reference)
; __global__ void __launch_bounds__(512, 2) mega_fwd(Args args) {
;     ...
;             const int hh = lane >> 3, jj = lane & 7;
;             const float* gqn = args.in[13]; const float* gkn = args.in[14];
;             f32x4 gq[4], gk[4];
; #pragma unroll
;             for (int i = 0; i < 4; ++i) { gq[i] = *(const f32x4*)(gqn + 16 * jj + 4 * i); gk[i] = *(const f32x4*)(gkn + 16 * jj + 4 * i); }
;             const f32x4 gq1 = *(const f32x4*)(gqn + 128 + 4 * jj), gq2 = *(const f32x4*)(gqn + 160 + 4 * jj), gk1 = *(const f32x4*)(gkn + 128 + 4 * jj), gk2 = *(const f32x4*)(gkn + 160 + 4 * jj);
;             float ifr[4];
; #pragma unroll
;             for (int e = 0; e < 4; ++e) ifr[e] = exp2f(-(float)(4 * jj + e) * (13.287712379549449f / 32.f));
;             const float qsc = 0.07216878364870322f * LOG2E;
;             u32x4 nqa0, nqa1, nka0, nka1; u32x2 nqr1, nqr2, nkr1, nkr2; int npos;
;     ...
;             if (gw < T) MLAP_LOAD(gw);
.LBB0_985:
	v_and_b32_e32 v240, 1, v184
	v_mul_u32_u24_e32 v240, 56, v240
	v_mov_b32_e32 v241, 0
	s_mov_b32 s94, 0xaaaaaaaa
	s_mov_b32 s95, 0xaaaaaaaa
	v_readlane_b32 s60, v238, 5
	v_and_b32_e32 v6, 7, v185
	v_mov_b32_e32 v81, 0
	v_readlane_b32 s70, v238, 15
	v_readlane_b32 s71, v238, 16
	v_readlane_b32 s72, v238, 17
	v_readlane_b32 s73, v238, 18
	s_cmpk_lt_i32 s82, 0x4000
	v_lshrrev_b32_e32 v2, 3, v184
	v_lshlrev_b32_e32 v0, 6, v6
	v_mov_b32_e32 v1, v81
	s_mov_b64 s[22:23], s[70:71]
	s_mov_b64 s[24:25], s[72:73]
	s_cselect_b64 s[2:3], -1, 0
	s_ashr_i32 s83, s82, 31
	s_mul_i32 s34, s82, 0xc00
	v_lshlrev_b32_e32 v80, 4, v6
	v_lshl_add_u64 v[82:83], s[22:23], 0, v[0:1]
	v_lshl_add_u64 v[84:85], s[24:25], 0, v[0:1]
	s_mul_hi_i32 s33, s82, 0xc00
	s_add_u32 s0, s6, s34
	v_mul_u32_u24_e32 v0, 0xc0, v2
	v_lshl_add_u64 v[86:87], s[22:23], 0, v[80:81]
	v_lshl_add_u64 v[88:89], s[24:25], 0, v[80:81]
	s_addc_u32 s1, s7, s33
	v_lshlrev_b32_e32 v80, 1, v0
	v_lshl_add_u64 v[0:1], s[0:1], 0, v[80:81]
	s_add_u32 s0, s8, s34
	s_addc_u32 s1, s9, s33
	v_lshl_add_u64 v[2:3], s[0:1], 0, v[80:81]
	s_mul_i32 s0, s82, 0x1800
	v_readlane_b32 s16, v238, 55
	v_lshlrev_b32_e32 v8, 2, v6
	s_mul_hi_i32 s1, s82, 0x1800
	v_readlane_b32 s17, v238, 56
	s_add_u32 s0, s16, s0
	v_lshlrev_b32_e32 v4, 5, v6
	v_mov_b32_e32 v5, v81
	v_lshlrev_b32_e32 v6, 3, v6
	v_mov_b32_e32 v7, v81
	s_addc_u32 s1, s17, s1
	v_lshl_add_u64 v[90:91], v[0:1], 0, v[4:5]
	v_lshl_add_u64 v[92:93], v[0:1], 0, v[6:7]
	v_lshl_add_u64 v[94:95], v[2:3], 0, v[4:5]
	v_cvt_f32_ubyte0_e32 v0, v8
	v_or_b32_e32 v3, 1, v8
	v_lshl_add_u64 v[96:97], s[0:1], 0, v[6:7]
	s_lshl_b64 s[0:1], s[82:83], 2
	v_mul_f32_e32 v1, 0xbed49a78, v0
	s_mov_b32 s16, 0xc2fc0000
	v_cvt_f32_ubyte0_e32 v3, v3
	s_add_u32 s22, s56, s0
	v_mov_b32_e32 v2, 0x42800000
	v_cmp_gt_f32_e32 vcc, s16, v1
	v_mul_f32_e32 v5, 0xbed49a78, v3
	s_addc_u32 s23, s57, s1
	v_cndmask_b32_e32 v1, 0, v2, vcc
	v_cmp_gt_f32_e64 s[0:1], s16, v5
	v_fmac_f32_e32 v1, 0xbed49a78, v0
	v_exp_f32_e32 v0, v1
	v_cndmask_b32_e64 v5, 0, v2, s[0:1]
	v_fmac_f32_e32 v5, 0xbed49a78, v3
	v_exp_f32_e32 v3, v5
	v_not_b32_e32 v1, 63
	v_cndmask_b32_e32 v5, 0, v1, vcc
	v_ldexp_f32 v142, v0, v5
	v_cndmask_b32_e64 v0, 0, v1, s[0:1]
	v_ldexp_f32 v143, v3, v0
	v_or_b32_e32 v0, 2, v8
	v_cvt_f32_ubyte0_e32 v0, v0
	v_mul_f32_e32 v3, 0xbed49a78, v0
	v_cmp_gt_f32_e32 vcc, s16, v3
	s_mov_b32 s46, 0x6dc9c883
	s_mov_b32 s14, 0
	v_cndmask_b32_e32 v3, 0, v2, vcc
	v_fmac_f32_e32 v3, 0xbed49a78, v0
	v_exp_f32_e32 v0, v3
	v_or_b32_e32 v3, 3, v8
	v_cvt_f32_ubyte0_e32 v3, v3
	v_mul_f32_e32 v5, 0xbed49a78, v3
	v_cmp_gt_f32_e64 s[0:1], s16, v5
	s_mul_hi_i32 s29, s96, 0x1800
	s_mul_i32 s28, s96, 0x1800
	v_cndmask_b32_e64 v2, 0, v2, s[0:1]
	v_fmac_f32_e32 v2, 0xbed49a78, v3
	v_cndmask_b32_e32 v3, 0, v1, vcc
	v_exp_f32_e32 v2, v2
	v_ldexp_f32 v144, v0, v3
	v_cndmask_b32_e64 v0, 0, v1, s[0:1]
	s_add_i32 s0, s82, s96
	s_ashr_i32 s1, s0, 31
	s_lshl_b64 s[16:17], s[0:1], 2
	s_mul_hi_i32 s1, s0, 0x1800
	s_add_u32 s24, s56, s16
	s_mul_i32 s16, s0, 0x1800
	v_mov_b32_e32 v99, s1
	s_mul_hi_i32 s1, s0, 0xc00
	s_mulk_i32 s0, 0xc00
	v_ldexp_f32 v145, v2, v0
	v_or_b32_e32 v0, s0, v4
	v_mov_b32_e32 v1, s1
	v_lshl_add_u64 v[100:101], v[0:1], 0, v[80:81]
	v_or_b32_e32 v0, s0, v6
	v_lshl_add_u64 v[102:103], v[0:1], 0, v[80:81]
	v_or_b32_e32 v0, s34, v4
	v_mov_b32_e32 v1, s33
	s_addc_u32 s25, s57, s17
	s_ashr_i32 s97, s96, 31
	v_lshl_add_u64 v[104:105], v[0:1], 0, v[80:81]
	v_or_b32_e32 v0, s34, v6
	s_lshl_b64 s[26:27], s[96:97], 2
	v_or_b32_e32 v98, s16, v6
	s_mul_hi_i32 s37, s96, 0xc00
	s_mul_i32 s36, s96, 0xc00
	v_lshl_add_u64 v[106:107], v[0:1], 0, v[80:81]
	s_mov_b64 s[42:43], 0x15800000
	s_mov_b32 s16, 0x15800000
	s_mov_b64 s[44:45], 0x18800000
	s_mov_b32 s17, 0x18800000
	s_mov_b32 s47, 0x3fc45f30
	s_mov_b32 s48, 0x3baaaaab
	s_mov_b32 s33, 0x800000
	v_cndmask_b32_e64 v146, 0, 1, s[2:3]
	v_mov_b32_e32 v80, 0x358637bd
	v_readlane_b32 s61, v238, 6
	v_readlane_b32 s62, v238, 7
	v_readlane_b32 s63, v238, 8
	v_readlane_b32 s64, v238, 9
	v_readlane_b32 s65, v238, 10
	v_readlane_b32 s66, v238, 11
	v_readlane_b32 s67, v238, 12
	v_readlane_b32 s68, v238, 13
	v_readlane_b32 s69, v238, 14
	v_readlane_b32 s74, v238, 19
	v_readlane_b32 s75, v238, 20
	s_branch .LBB0_988

; __global__ void __launch_bounds__(512, 2) mega_fwd(Args args) {
;     ...
;                 const float pos = (float)npos;
;                 if (m + NGW < T) MLAP_LOAD(m + NGW);
;                 float cs[4], sn[4];
; #pragma unroll
;                 for (int e = 0; e < 4; ++e) { const float ang = pos * ifr[e]; double rv = (double)ang * 0.15915494309189535; rv -= rint(rv); const float rf = (float)rv; cs[e] = __builtin_amdgcn_cosf(rf); sn[e] = __builtin_amdgcn_sinf(rf); }
.LBB0_994:
	v_cvt_f32_i32_e32 v148, v126
	v_and_b32_e32 v171, 0xffff0000, v72
	v_and_b32_e32 v195, 0xffff0000, v64
	v_lshlrev_b32_e32 v170, 16, v72
	v_mul_f32_e32 v130, v143, v148
	v_mul_f32_e32 v126, v142, v148
	v_cvt_f64_f32_e32 v[134:135], v130
	v_cvt_f64_f32_e32 v[126:127], v126
	v_mul_f64 v[136:137], v[134:135], s[46:47]
	v_mul_f64 v[130:131], v[126:127], s[46:47]
	v_rndne_f64_e32 v[136:137], v[136:137]
	v_lshlrev_b32_e32 v194, 16, v64
	v_mov_b32_e32 v196, v195
	v_mov_b32_e32 v197, v171
	v_rndne_f64_e32 v[130:131], v[130:131]
	v_fma_f64 v[134:135], v[134:135], s[46:47], -v[136:137]
	v_lshlrev_b32_e32 v168, 16, v73
	v_lshlrev_b32_e32 v182, 16, v69
	v_and_b32_e32 v183, 0xffff0000, v69
	v_lshlrev_b32_e32 v186, 16, v68
	v_and_b32_e32 v187, 0xffff0000, v68
	v_lshlrev_b32_e32 v192, 16, v65
	v_mov_b32_e32 v68, v194
	v_mov_b32_e32 v69, v170
	v_pk_mul_f32 v[196:197], v[196:197], v[196:197]
	v_fma_f64 v[126:127], v[126:127], s[46:47], -v[130:131]
	v_cvt_f32_f64_e32 v131, v[134:135]
	v_mul_f32_e32 v134, v144, v148
	v_and_b32_e32 v169, 0xffff0000, v73
	v_and_b32_e32 v193, 0xffff0000, v65
	v_mov_b32_e32 v64, v192
	v_mov_b32_e32 v65, v168
	v_pk_fma_f32 v[68:69], v[68:69], v[68:69], v[196:197]
	v_cvt_f64_f32_e32 v[134:135], v134
	v_lshlrev_b32_e32 v166, 16, v74
	v_lshlrev_b32_e32 v188, 16, v67
	v_and_b32_e32 v189, 0xffff0000, v67
	v_lshlrev_b32_e32 v190, 16, v66
	v_and_b32_e32 v191, 0xffff0000, v66
	v_mov_b32_e32 v66, v193
	v_mov_b32_e32 v67, v169
	v_pk_fma_f32 v[64:65], v[64:65], v[64:65], v[68:69]
	v_mul_f64 v[136:137], v[134:135], s[46:47]
	v_and_b32_e32 v167, 0xffff0000, v74
	v_mov_b32_e32 v206, v190
	v_mov_b32_e32 v207, v166
	v_pk_fma_f32 v[64:65], v[66:67], v[66:67], v[64:65]
	v_rndne_f64_e32 v[136:137], v[136:137]
	v_lshlrev_b32_e32 v164, 16, v76
	v_and_b32_e32 v165, 0xffff0000, v76
	v_lshlrev_b32_e32 v76, 16, v75
	v_mov_b32_e32 v208, v191
	v_mov_b32_e32 v209, v167
	v_pk_fma_f32 v[64:65], v[206:207], v[206:207], v[64:65]
	v_fma_f64 v[134:135], v[134:135], s[46:47], -v[136:137]
	v_lshlrev_b32_e32 v162, 16, v77
	v_and_b32_e32 v163, 0xffff0000, v77
	v_and_b32_e32 v77, 0xffff0000, v75
	v_mov_b32_e32 v202, v188
	v_mov_b32_e32 v203, v76
	v_pk_fma_f32 v[64:65], v[208:209], v[208:209], v[64:65]
	v_cvt_f32_f64_e32 v135, v[134:135]
	v_mov_b32_e32 v204, v189
	v_mov_b32_e32 v205, v77
	v_pk_fma_f32 v[64:65], v[202:203], v[202:203], v[64:65]
	v_cos_f32_e32 v134, v135
	v_sin_f32_e32 v136, v135
	v_mul_f32_e32 v135, v145, v148
	v_mov_b32_e32 v198, v186
	v_mov_b32_e32 v199, v164
	v_pk_fma_f32 v[64:65], v[204:205], v[204:205], v[64:65]
	v_cvt_f64_f32_e32 v[148:149], v135
	v_mov_b32_e32 v200, v187
	v_mov_b32_e32 v201, v165
	v_pk_fma_f32 v[64:65], v[198:199], v[198:199], v[64:65]
	v_mul_f64 v[150:151], v[148:149], s[46:47]
	v_lshlrev_b32_e32 v160, 16, v78
	v_and_b32_e32 v161, 0xffff0000, v78
	v_lshlrev_b32_e32 v180, 16, v70
	v_and_b32_e32 v181, 0xffff0000, v70
	v_mov_b32_e32 v68, v182
	v_mov_b32_e32 v69, v162
	v_pk_fma_f32 v[64:65], v[200:201], v[200:201], v[64:65]
	v_rndne_f64_e32 v[150:151], v[150:151]
	v_lshlrev_b32_e32 v156, 16, v79
	v_and_b32_e32 v157, 0xffff0000, v79
	v_pk_mul_f32 v[78:79], v[160:161], v[160:161]
	v_lshlrev_b32_e32 v176, 16, v71
	v_and_b32_e32 v177, 0xffff0000, v71
	v_pk_mul_f32 v[70:71], v[180:181], v[180:181]
	v_mov_b32_e32 v196, v183
	v_mov_b32_e32 v197, v163
	v_pk_fma_f32 v[64:65], v[68:69], v[68:69], v[64:65]
	v_fma_f64 v[148:149], v[148:149], s[46:47], -v[150:151]
	v_pk_fma_f32 v[64:65], v[196:197], v[196:197], v[64:65]
	v_mov_b32_e32 v66, v70
	v_mov_b32_e32 v67, v78
	v_cvt_f32_f64_e32 v137, v[148:149]
	v_lshlrev_b32_e32 v148, 16, v141
	v_and_b32_e32 v149, 0xffff0000, v141
	v_lshlrev_b32_e32 v154, 16, v140
	v_and_b32_e32 v155, 0xffff0000, v140
	v_lshlrev_b32_e32 v140, 16, v138
	v_and_b32_e32 v141, 0xffff0000, v138
	v_pk_mul_f32 v[158:159], v[156:157], v[156:157]
	v_lshlrev_b32_e32 v72, 16, v133
	v_and_b32_e32 v73, 0xffff0000, v133
	v_lshlrev_b32_e32 v174, 16, v132
	v_and_b32_e32 v175, 0xffff0000, v132
	v_lshlrev_b32_e32 v132, 16, v128
	v_and_b32_e32 v133, 0xffff0000, v128
	v_pk_mul_f32 v[178:179], v[176:177], v[176:177]
	v_pk_add_f32 v[64:65], v[64:65], v[66:67]
	v_mov_b32_e32 v78, v71
	v_lshlrev_b32_e32 v150, 16, v139
	v_and_b32_e32 v151, 0xffff0000, v139
	v_pk_mul_f32 v[138:139], v[140:141], v[140:141]
	v_lshlrev_b32_e32 v74, 16, v129
	v_and_b32_e32 v75, 0xffff0000, v129
	v_pk_mul_f32 v[128:129], v[132:133], v[132:133]
	v_pk_add_f32 v[64:65], v[64:65], v[78:79]
	v_mov_b32_e32 v66, v178
	v_mov_b32_e32 v67, v158
	v_pk_fma_f32 v[138:139], v[154:155], v[154:155], v[138:139]
	v_pk_fma_f32 v[128:129], v[174:175], v[174:175], v[128:129]
	v_pk_add_f32 v[64:65], v[64:65], v[66:67]
	v_mov_b32_e32 v158, v179
	v_pk_mul_f32 v[152:153], v[150:151], v[150:151]
	v_pk_mul_f32 v[172:173], v[74:75], v[74:75]
	v_pk_add_f32 v[64:65], v[64:65], v[158:159]
	v_mov_b32_e32 v66, v128
	v_mov_b32_e32 v67, v138
	v_pk_fma_f32 v[152:153], v[148:149], v[148:149], v[152:153]
	v_pk_fma_f32 v[172:173], v[72:73], v[72:73], v[172:173]
	v_pk_add_f32 v[64:65], v[64:65], v[66:67]
	v_mov_b32_e32 v138, v129
	v_pk_add_f32 v[64:65], v[64:65], v[138:139]
	v_mov_b32_e32 v66, v172
	v_mov_b32_e32 v67, v152
	v_pk_add_f32 v[64:65], v[64:65], v[66:67]
	v_mov_b32_e32 v152, v173
	v_pk_add_f32 v[64:65], v[64:65], v[152:153]
	v_cvt_f32_f64_e32 v127, v[126:127]
	v_cos_f32_e32 v126, v127
	v_mov_b32_dpp v67, v65 quad_perm:[1,0,3,2] row_mask:0xf bank_mask:0xf bound_ctrl:1
	v_mov_b32_dpp v66, v64 quad_perm:[1,0,3,2] row_mask:0xf bank_mask:0xf bound_ctrl:1
	v_pk_add_f32 v[64:65], v[64:65], v[66:67]
	v_sin_f32_e32 v130, v127
	v_cos_f32_e32 v127, v131
; __global__ void __launch_bounds__(512, 2) mega_fwd(Args args) {
;     ...
;                 MLAP_ONE(qa0, qa1, qr1, qr2, gq, gq1, gq2, qsc, qp);
	v_mov_b32_dpp v67, v65 quad_perm:[2,3,0,1] row_mask:0xf bank_mask:0xf bound_ctrl:1
	v_mov_b32_dpp v66, v64 quad_perm:[2,3,0,1] row_mask:0xf bank_mask:0xf bound_ctrl:1
	v_pk_add_f32 v[64:65], v[64:65], v[66:67]
	v_sin_f32_e32 v131, v131
	v_cos_f32_e32 v135, v137
	v_mov_b32_dpp v67, v65 row_half_mirror row_mask:0xf bank_mask:0xf bound_ctrl:1
	v_mov_b32_dpp v66, v64 row_half_mirror row_mask:0xf bank_mask:0xf bound_ctrl:1
	v_pk_add_f32 v[64:65], v[64:65], v[66:67]
	v_sin_f32_e32 v137, v137
	v_pk_fma_f32 v[78:79], v[64:65], s[48:49], v[80:81] op_sel_hi:[1,0,0]
	v_lshl_add_u64 v[128:129], s[86:87], 0, v[116:117]
	v_mul_f32_e32 v64, 0x4b800000, v79
	v_cmp_gt_f32_e32 vcc, s33, v79
	v_lshl_add_u64 v[138:139], s[86:87], 0, v[114:115]
	s_add_u32 s50, s50, s26
	v_cndmask_b32_e32 v64, v79, v64, vcc
	v_rsq_f32_e32 v64, v64
	s_addc_u32 s51, s51, s27
	v_lshl_add_u64 v[124:125], v[124:125], 0, s[28:29]
	v_lshl_add_u64 v[122:123], v[122:123], 0, s[36:37]
	v_mul_f32_e32 v65, 0x45800000, v64
	v_cndmask_b32_e32 v64, v64, v65, vcc
	v_mul_f32_e32 v152, 0x3dd53b94, v64
	v_pk_mul_f32 v[64:65], v[152:153], v[170:171] op_sel_hi:[0,1]
	v_pk_mul_f32 v[66:67], v[152:153], v[168:169] op_sel_hi:[0,1]
	v_pk_mul_f32 v[64:65], v[12:13], v[64:65]
	v_pk_mul_f32 v[66:67], v[14:15], v[66:67]
	v_cvt_pk_bf16_f32 v64, v64, v65
	v_cvt_pk_bf16_f32 v65, v66, v67
	v_pk_mul_f32 v[66:67], v[152:153], v[166:167] op_sel_hi:[0,1]
	v_pk_mul_f32 v[68:69], v[152:153], v[76:77] op_sel_hi:[0,1]
	v_pk_mul_f32 v[66:67], v[8:9], v[66:67]
	v_pk_mul_f32 v[68:69], v[10:11], v[68:69]
	v_cvt_pk_bf16_f32 v66, v66, v67
	v_cvt_pk_bf16_f32 v67, v68, v69
	v_pk_mul_f32 v[68:69], v[152:153], v[164:165] op_sel_hi:[0,1]
	v_pk_mul_f32 v[70:71], v[152:153], v[162:163] op_sel_hi:[0,1]
	v_pk_mul_f32 v[68:69], v[4:5], v[68:69]
	v_pk_mul_f32 v[70:71], v[6:7], v[70:71]
	v_cvt_pk_bf16_f32 v68, v68, v69
	v_cvt_pk_bf16_f32 v69, v70, v71
	v_pk_mul_f32 v[70:71], v[152:153], v[160:161] op_sel_hi:[0,1]
	v_pk_mul_f32 v[76:77], v[152:153], v[156:157] op_sel_hi:[0,1]
	v_pk_mul_f32 v[70:71], v[0:1], v[70:71]
	v_pk_mul_f32 v[76:77], v[2:3], v[76:77]
	v_pk_mul_f32 v[140:141], v[152:153], v[140:141] op_sel_hi:[0,1]
	v_cvt_pk_bf16_f32 v70, v70, v71
	v_cvt_pk_bf16_f32 v71, v76, v77
	v_pk_mul_f32 v[76:77], v[152:153], v[154:155] op_sel_hi:[0,1]
	v_pk_mul_f32 v[140:141], v[36:37], v[140:141]
	v_pk_mul_f32 v[76:77], v[32:33], v[76:77]
	v_pk_mul_f32 v[154:155], v[140:141], v[130:131]
	v_lshl_add_u64 v[120:121], v[120:121], 0, s[36:37]
	v_pk_fma_f32 v[154:155], v[76:77], v[126:127], v[154:155] neg_lo:[0,0,1] neg_hi:[0,0,1]
	v_pk_mul_f32 v[76:77], v[76:77], v[130:131]
	v_lshl_add_u64 v[116:117], v[116:117], 0, s[36:37]
	v_pk_fma_f32 v[76:77], v[126:127], v[140:141], v[76:77]
	v_pk_mul_f32 v[140:141], v[152:153], v[148:149] op_sel_hi:[0,1]
	v_pk_mul_f32 v[148:149], v[152:153], v[150:151] op_sel_hi:[0,1]
	v_pk_mul_f32 v[148:149], v[38:39], v[148:149]
	v_pk_mul_f32 v[140:141], v[34:35], v[140:141]
	v_pk_mul_f32 v[150:151], v[148:149], v[136:137]
	v_cvt_pk_bf16_f32 v76, v76, v77
	v_pk_fma_f32 v[150:151], v[140:141], v[134:135], v[150:151] neg_lo:[0,0,1] neg_hi:[0,0,1]
	v_pk_mul_f32 v[140:141], v[140:141], v[136:137]
	v_lshl_add_u64 v[114:115], v[114:115], 0, s[36:37]
	v_pk_fma_f32 v[140:141], v[134:135], v[148:149], v[140:141]
	v_cvt_pk_bf16_f32 v148, v154, v155
	v_cvt_pk_bf16_f32 v77, v140, v141
	v_add_co_u32_e32 v140, vcc, s16, v128
	v_cvt_pk_bf16_f32 v149, v150, v151
	s_nop 0
	v_addc_co_u32_e32 v141, vcc, 0, v129, vcc
	global_store_dwordx4 v[140:141], v[64:67], off
	global_store_dwordx4 v[140:141], v[68:71], off offset:16
	v_cmp_gt_f32_e32 vcc, s33, v78
	v_mul_f32_e32 v64, 0x4b800000, v78
	s_nop 0
	v_cndmask_b32_e32 v64, v78, v64, vcc
	v_rsq_f32_e32 v66, v64
	v_add_co_u32_e64 v64, s[0:1], s16, v138
	s_nop 1
	v_addc_co_u32_e64 v65, s[0:1], 0, v139, s[0:1]
	s_nop 1
	v_mov_b32_dpp v248, v148 quad_perm:[1,0,3,2] row_mask:0xf bank_mask:0xf
	v_mov_b32_dpp v249, v149 quad_perm:[1,0,3,2] row_mask:0xf bank_mask:0xf
	v_mov_b32_dpp v250, v76 quad_perm:[1,0,3,2] row_mask:0xf bank_mask:0xf
; __global__ void __launch_bounds__(512, 2) mega_fwd(Args args) {
;     ...
;             for (int m = gw; m < T; m += NGW) {
;                 bf16_t* qp = Qb + (size_t)m * 1536 + hh * 192; bf16_t* kp = Kb + (size_t)m * 1536 + hh * 192;
;                 const u32x4 qa0 = nqa0, qa1 = nqa1, ka0 = nka0, ka1 = nka1; const u32x2 qr1 = nqr1, qr2 = nqr2, kr1 = nkr1, kr2 = nkr2;
;                 const float pos = (float)npos;
;                 if (m + NGW < T) MLAP_LOAD(m + NGW);
;     ...
;                 MLAP_ONE(qa0, qa1, qr1, qr2, gq, gq1, gq2, qsc, qp);
;                 MLAP_ONE(ka0, ka1, kr1, kr2, gk, gk1, gk2, 1.f, kp);
	v_mov_b32_dpp v251, v77 quad_perm:[1,0,3,2] row_mask:0xf bank_mask:0xf
	v_cndmask_b32_e64 v244, v148, v250, s[94:95]
	v_cndmask_b32_e64 v245, v149, v251, s[94:95]
	v_cndmask_b32_e64 v246, v248, v76, s[94:95]
	v_cndmask_b32_e64 v247, v249, v77, s[94:95]
	v_lshl_add_u64 v[64:65], v[64:65], 0, v[240:241]
	global_store_dwordx4 v[64:65], v[244:247], off offset:256
	v_mul_f32_e32 v64, 0x45800000, v66
	v_cndmask_b32_e32 v76, v66, v64, vcc
	v_pk_mul_f32 v[64:65], v[76:77], v[194:195] op_sel_hi:[0,1]
	v_pk_mul_f32 v[66:67], v[76:77], v[192:193] op_sel_hi:[0,1]
	v_pk_mul_f32 v[64:65], v[28:29], v[64:65]
	v_pk_mul_f32 v[66:67], v[30:31], v[66:67]
	v_cvt_pk_bf16_f32 v64, v64, v65
	v_cvt_pk_bf16_f32 v65, v66, v67
	v_pk_mul_f32 v[66:67], v[76:77], v[190:191] op_sel_hi:[0,1]
	v_pk_mul_f32 v[68:69], v[76:77], v[188:189] op_sel_hi:[0,1]
	v_pk_mul_f32 v[66:67], v[24:25], v[66:67]
	v_pk_mul_f32 v[68:69], v[26:27], v[68:69]
	v_cvt_pk_bf16_f32 v66, v66, v67
	v_cvt_pk_bf16_f32 v67, v68, v69
	v_pk_mul_f32 v[68:69], v[76:77], v[186:187] op_sel_hi:[0,1]
	v_pk_mul_f32 v[70:71], v[76:77], v[182:183] op_sel_hi:[0,1]
	v_pk_mul_f32 v[68:69], v[20:21], v[68:69]
	v_pk_mul_f32 v[70:71], v[22:23], v[70:71]
	v_cvt_pk_bf16_f32 v68, v68, v69
	v_cvt_pk_bf16_f32 v69, v70, v71
	v_pk_mul_f32 v[70:71], v[76:77], v[180:181] op_sel_hi:[0,1]
	v_pk_mul_f32 v[78:79], v[76:77], v[176:177] op_sel_hi:[0,1]
	v_pk_mul_f32 v[74:75], v[76:77], v[74:75] op_sel_hi:[0,1]
	v_pk_mul_f32 v[70:71], v[16:17], v[70:71]
	v_pk_mul_f32 v[78:79], v[18:19], v[78:79]
	v_pk_mul_f32 v[72:73], v[76:77], v[72:73] op_sel_hi:[0,1]
	v_pk_mul_f32 v[74:75], v[46:47], v[74:75]
	v_cvt_pk_bf16_f32 v70, v70, v71
	v_cvt_pk_bf16_f32 v71, v78, v79
	v_pk_mul_f32 v[78:79], v[76:77], v[174:175] op_sel_hi:[0,1]
	v_pk_mul_f32 v[132:133], v[76:77], v[132:133] op_sel_hi:[0,1]
	v_pk_mul_f32 v[72:73], v[42:43], v[72:73]
	v_pk_mul_f32 v[76:77], v[74:75], v[136:137]
	v_pk_mul_f32 v[132:133], v[44:45], v[132:133]
	v_pk_fma_f32 v[76:77], v[72:73], v[134:135], v[76:77] neg_lo:[0,0,1] neg_hi:[0,0,1]
	v_pk_mul_f32 v[72:73], v[72:73], v[136:137]
	v_pk_mul_f32 v[78:79], v[40:41], v[78:79]
	v_pk_fma_f32 v[72:73], v[134:135], v[74:75], v[72:73]
	v_cvt_pk_bf16_f32 v75, v76, v77
	v_cvt_pk_bf16_f32 v77, v72, v73
	v_add_co_u32_e32 v72, vcc, s17, v128
	v_pk_mul_f32 v[140:141], v[132:133], v[130:131]
	s_nop 0
	v_addc_co_u32_e32 v73, vcc, 0, v129, vcc
	global_store_dwordx4 v[72:73], v[64:67], off
	global_store_dwordx4 v[72:73], v[68:71], off offset:16
	v_pk_fma_f32 v[140:141], v[78:79], v[126:127], v[140:141] neg_lo:[0,0,1] neg_hi:[0,0,1]
	v_add_co_u32_e32 v64, vcc, s17, v138
	v_pk_mul_f32 v[78:79], v[78:79], v[130:131]
	s_nop 0
	v_addc_co_u32_e32 v65, vcc, 0, v139, vcc
	v_pk_fma_f32 v[78:79], v[126:127], v[132:133], v[78:79]
	v_cvt_pk_bf16_f32 v74, v140, v141
	s_and_b64 vcc, exec, s[52:53]
	v_cvt_pk_bf16_f32 v76, v78, v79
	s_nop 1
	v_mov_b32_dpp v248, v74 quad_perm:[1,0,3,2] row_mask:0xf bank_mask:0xf
	v_mov_b32_dpp v249, v75 quad_perm:[1,0,3,2] row_mask:0xf bank_mask:0xf
	v_mov_b32_dpp v250, v76 quad_perm:[1,0,3,2] row_mask:0xf bank_mask:0xf
	v_mov_b32_dpp v251, v77 quad_perm:[1,0,3,2] row_mask:0xf bank_mask:0xf
	v_cndmask_b32_e64 v244, v74, v250, s[94:95]
	v_cndmask_b32_e64 v245, v75, v251, s[94:95]
	v_cndmask_b32_e64 v246, v248, v76, s[94:95]
	v_cndmask_b32_e64 v247, v249, v77, s[94:95]
	v_lshl_add_u64 v[64:65], v[64:65], 0, v[240:241]
	global_store_dwordx4 v[64:65], v[244:247], off offset:256
	s_cbranch_vccnz .LBB0_987
	s_waitcnt vmcnt(14)
	v_mov_b64_e32 v[74:75], v[50:51]
	s_waitcnt vmcnt(13)
	v_mov_b64_e32 v[78:79], v[54:55]
	s_waitcnt vmcnt(10)
	v_mov_b64_e32 v[66:67], v[58:59]
	s_waitcnt vmcnt(9)
	v_mov_b64_e32 v[70:71], v[62:63]
	v_mov_b64_e32 v[72:73], v[48:49]
	v_mov_b64_e32 v[76:77], v[52:53]
	v_mov_b64_e32 v[64:65], v[56:57]
	v_mov_b64_e32 v[68:69], v[60:61]
	v_mov_b64_e32 v[140:141], v[108:109]
	v_mov_b64_e32 v[138:139], v[110:111]
	s_waitcnt vmcnt(8)
	v_mov_b64_e32 v[132:133], v[112:113]
	s_waitcnt vmcnt(7)
	v_mov_b64_e32 v[128:129], v[118:119]
	s_waitcnt vmcnt(6)
	v_mov_b32_e32 v126, v147
	s_branch .LBB0_992
